# scan operand LDS-DMA with default cache policy instead of nt
# speedup vs baseline: 1.0534x; 1.0070x over previous
; #define SCAN_ISSUE(n, slot) do { const unsigned char* s_ = src + (size_t)(n) * step_stride; LAS unsigned char* d_ = lds + (slot) * SR_SLOT + p0 * 1024; \
;         _Pragma("unroll") for (int i_ = 0; i_ < 7; ++i_) glds16_asm(s_ + i_ * 1024, d_ + i_ * 1024, true  ); \
;         if (lw < 2) glds16_asm(s_ + 7 * 1024, d_ + 7 * 1024, true); } while (0)
; #define SCAN_ZISSUE(n) do { const unsigned char* z_ = zsrc + (size_t)(n) * 64 * 2048; LAS unsigned char* d_ = lds + ZT_OFF + ((n) & 1) * 8192 + (2 * lw) * 1024; \
;         glds16_asm(z_, d_, false); glds16_asm(z_ + 8 * 2048, d_ + 1024, false); } while (0)
; __device__ __forceinline__ void scan_prompt_wg(const Params& P, LAS unsigned char* lds, int s, int h, int wave, int lane) {
;     ...
;     if (wave >= 4) {
;         const int lw = wave - 4;
;         const int np = (lw < 2) ? 8 : 7, p0 = (lw < 2) ? 8 * lw : 16 + 7 * (lw - 2);
;         const unsigned char* src = ops0 + (size_t)p0 * 1024 + lane * 16;
;     ...
;         const int ftid = lw * 64 + lane, ft = ftid >> 2, fp = ftid & 3;
;         float gg[16];
; #pragma unroll
;         for (int i = 0; i < 16; ++i) gg[i] = P.gdn_g[16 * fp + i];
;         bf16* Mr = (bf16*)(P.ws + WS_MIX) + ((size_t)s * TP + ft) * 1024 + h * 64 + 16 * fp;
;         const unsigned char* zsrc = (const unsigned char*)((const bf16*)(P.ws + WS_Z) + ((size_t)s * TP + 16 * lw + (lane >> 3)) * 1024 + h * 64) + (lane & 7) * 16;
;     ...
; #pragma unroll
;         for (int i = 0; i < 16; ++i) asm volatile("" : "+v"(gg[i]));
;         SCAN_ZISSUE(0);
;         SCAN_ISSUE(0, 0); SCAN_ISSUE(1, 1); SCAN_ISSUE(2, 2);
.LBB0_654:
	s_and_b64 vcc, exec, s[16:17]
	v_readlane_b32 s96, v247, 24
	s_cbranch_vccz .LBB0_683
	v_and_b32_e32 v28, 3, v35
	v_lshlrev_b32_e32 v19, 6, v28
	global_load_dwordx4 v[2:5], v19, s[46:47]
	global_load_dwordx4 v[6:9], v19, s[46:47] offset:16
	global_load_dwordx4 v[10:13], v19, s[46:47] offset:32
	global_load_dwordx4 v[14:17], v19, s[46:47] offset:48
	s_lshl_b32 s0, s2, 7
	s_add_u32 s10, s10, s0
	s_addc_u32 s11, s11, 0
	s_lshl_b64 s[14:15], s[8:9], 13
	s_add_i32 s17, s33, -4
	s_cmp_gt_u32 s33, 5
	v_mov_b32_e32 v25, 0
	s_cselect_b64 s[8:9], -1, 0
	s_lshl_b32 s16, s17, 4
	v_mov_b32_e32 v19, v25
	s_add_u32 s0, s14, s16
	v_lshrrev_b32_e32 v24, 3, v164
	v_lshl_add_u64 v[20:21], s[12:13], 0, v[18:19]
	s_addc_u32 s12, s15, 0
	s_lshl_b32 s13, s17, 11
	s_mul_i32 s29, s33, 7
	v_or_b32_e32 v26, s0, v24
	s_add_i32 s0, s13, 0
	s_lshl_b32 s36, s17, 3
	s_sub_i32 s29, s29, 26
	v_mov_b32_e32 v27, s12
	s_add_i32 s41, s0, 0x22200
	s_add_i32 s37, s0, 0x22600
	v_lshlrev_b64 v[26:27], 11, v[26:27]
	s_cmp_lt_u32 s33, 6
	v_lshl_add_u64 v[26:27], s[10:11], 0, v[26:27]
	s_cselect_b64 s[10:11], -1, 0
	s_and_b64 s[12:13], s[10:11], exec
	s_mov_b32 s1, 0
	s_cselect_b32 s0, s36, s29
	v_and_b32_e32 v22, 0x70, v18
	v_mov_b32_e32 v23, v25
	s_lshl_b64 s[12:13], s[0:1], 10
	s_mov_b64 s[20:21], 0x400
	v_lshl_add_u64 v[30:31], v[26:27], 0, v[22:23]
	v_lshl_add_u64 v[26:27], v[20:21], 0, s[12:13]
	s_mov_b64 s[18:19], 0x4000
	v_lshl_add_u64 v[36:37], v[26:27], 0, s[20:21]
	v_lshl_add_u64 v[32:33], v[30:31], 0, s[18:19]
	s_lshl_b32 s0, s0, 10
	s_add_i32 s42, s0, 0
	s_mov_b64 s[22:23], 0x800
	s_add_i32 s0, s42, 0x400
	s_mov_b64 s[24:25], 0xc00
	v_lshl_add_u64 v[38:39], v[26:27], 0, s[22:23]
	s_add_i32 s1, s42, 0x800
	s_mov_b64 s[30:31], 0x1000
	v_lshl_add_u64 v[40:41], v[26:27], 0, s[24:25]
	s_add_i32 s18, s42, 0xc00
	s_mov_b64 s[34:35], 0x1400
	v_lshl_add_u64 v[42:43], v[26:27], 0, s[30:31]
	s_add_i32 s19, s42, 0x1000
	v_lshl_add_u64 v[44:45], v[26:27], 0, s[34:35]
	s_and_b64 vcc, exec, s[8:9]
	s_waitcnt vmcnt(3)
	s_waitcnt vmcnt(0)
	v_mov_b32_e32 v21, v14
	v_mov_b32_e32 v20, v15
	s_mov_b32 s20, m0
	s_mov_b32 m0, s41
	s_nop 0
	global_load_lds_dwordx4 v[30:31], off
	s_mov_b32 m0, s20
	s_nop 0
	s_mov_b32 s20, m0
	s_mov_b32 m0, s37
	s_nop 0
	global_load_lds_dwordx4 v[32:33], off
	s_mov_b32 m0, s20
	s_nop 0
	s_mov_b32 s20, m0
	s_mov_b32 m0, s42
	s_nop 0
	global_load_lds_dwordx4 v[26:27], off
	s_mov_b32 m0, s20
	s_nop 0
	s_mov_b32 s20, m0
	s_mov_b32 m0, s0
	s_nop 0
	global_load_lds_dwordx4 v[36:37], off
	s_mov_b32 m0, s20
	s_mov_b32 s0, m0
	s_mov_b32 m0, s1
	s_nop 0
	global_load_lds_dwordx4 v[38:39], off
	s_mov_b32 m0, s0
	s_nop 0
	s_mov_b32 s0, m0
	s_mov_b32 m0, s18
	s_nop 0
	global_load_lds_dwordx4 v[40:41], off
	s_mov_b32 m0, s0
	s_nop 0
	s_mov_b32 s0, m0
	s_mov_b32 m0, s19
	s_nop 0
	global_load_lds_dwordx4 v[42:43], off
	s_mov_b32 m0, s0
	s_add_i32 s0, s42, 0x1400
	s_mov_b32 s1, m0
	s_mov_b32 m0, s0
	s_nop 0
	global_load_lds_dwordx4 v[44:45], off
	s_mov_b32 m0, s1
	s_mov_b64 s[0:1], 0x1800
	v_lshl_add_u64 v[14:15], v[26:27], 0, s[0:1]
	s_add_i32 s0, s42, 0x1800
	s_mov_b32 s1, m0
	s_mov_b32 m0, s0
	s_nop 0
	global_load_lds_dwordx4 v[14:15], off
	s_mov_b32 m0, s1
	s_cbranch_vccnz .LBB0_657
	s_mov_b64 s[0:1], 0x1c00
	v_lshl_add_u64 v[14:15], v[26:27], 0, s[0:1]
	s_add_i32 s0, s42, 0x1c00
	s_mov_b32 s1, m0
	s_mov_b32 m0, s0
	s_nop 0
	global_load_lds_dwordx4 v[14:15], off
	s_mov_b32 m0, s1
; #define SCAN_BAR() do { asm volatile("" ::: "memory"); __builtin_amdgcn_s_barrier(); asm volatile("" ::: "memory"); } while (0)
; #define SCAN_ISSUE(n, slot) do { const unsigned char* s_ = src + (size_t)(n) * step_stride; LAS unsigned char* d_ = lds + (slot) * SR_SLOT + p0 * 1024; \
;         _Pragma("unroll") for (int i_ = 0; i_ < 7; ++i_) glds16_asm(s_ + i_ * 1024, d_ + i_ * 1024, true  ); \
;         if (lw < 2) glds16_asm(s_ + 7 * 1024, d_ + 7 * 1024, true); } while (0)
; #define SCAN_ZISSUE(n) do { const unsigned char* z_ = zsrc + (size_t)(n) * 64 * 2048; LAS unsigned char* d_ = lds + ZT_OFF + ((n) & 1) * 8192 + (2 * lw) * 1024; \
;         glds16_asm(z_, d_, false); glds16_asm(z_ + 8 * 2048, d_ + 1024, false); } while (0)
; __device__ __forceinline__ void scan_prompt_wg(const Params& P, LAS unsigned char* lds, int s, int h, int wave, int lane) {
;     ...
;         const int ftid = lw * 64 + lane, ft = ftid >> 2, fp = ftid & 3;
;         float gg[16];
; #pragma unroll
;         for (int i = 0; i < 16; ++i) gg[i] = P.gdn_g[16 * fp + i];
;         bf16* Mr = (bf16*)(P.ws + WS_MIX) + ((size_t)s * TP + ft) * 1024 + h * 64 + 16 * fp;
;         const unsigned char* zsrc = (const unsigned char*)((const bf16*)(P.ws + WS_Z) + ((size_t)s * TP + 16 * lw + (lane >> 3)) * 1024 + h * 64) + (lane & 7) * 16;
;     ...
; #pragma unroll
;         for (int i = 0; i < 16; ++i) asm volatile("" : "+v"(gg[i]));
;         SCAN_ZISSUE(0);
;         SCAN_ISSUE(0, 0); SCAN_ISSUE(1, 1); SCAN_ISSUE(2, 2);
;         if (lw < 2) asm volatile("s_waitcnt vmcnt(16)" ::: "memory"); else asm volatile("s_waitcnt vmcnt(14)" ::: "memory");
;         SCAN_BAR();
.LBB0_657:
	s_mov_b64 s[0:1], 0x50000
	v_lshl_add_u64 v[14:15], v[26:27], 0, s[0:1]
	s_add_i32 s0, s42, 0x7800
	s_mov_b32 s1, m0
	s_mov_b32 m0, s0
	s_nop 0
	global_load_lds_dwordx4 v[14:15], off
	s_mov_b32 m0, s1
	s_mov_b64 s[0:1], 0x50400
	v_lshl_add_u64 v[14:15], v[26:27], 0, s[0:1]
	s_add_i32 s0, s42, 0x7c00
	s_mov_b32 s1, m0
	s_mov_b32 m0, s0
	s_nop 0
	global_load_lds_dwordx4 v[14:15], off
	s_mov_b32 m0, s1
	s_mov_b64 s[0:1], 0x50800
	v_lshl_add_u64 v[14:15], v[26:27], 0, s[0:1]
	s_add_i32 s0, s42, 0x8000
	s_mov_b32 s1, m0
	s_mov_b32 m0, s0
	s_nop 0
	global_load_lds_dwordx4 v[14:15], off
	s_mov_b32 m0, s1
	s_mov_b64 s[0:1], 0x50c00
	v_lshl_add_u64 v[14:15], v[26:27], 0, s[0:1]
	s_add_i32 s0, s42, 0x8400
	s_mov_b32 s1, m0
	s_mov_b32 m0, s0
	s_nop 0
	global_load_lds_dwordx4 v[14:15], off
	s_mov_b32 m0, s1
	s_mov_b64 s[0:1], 0x51000
	v_lshl_add_u64 v[14:15], v[26:27], 0, s[0:1]
	s_add_i32 s0, s42, 0x8800
	s_mov_b32 s1, m0
	s_mov_b32 m0, s0
	s_nop 0
	global_load_lds_dwordx4 v[14:15], off
	s_mov_b32 m0, s1
	s_mov_b64 s[0:1], 0x51400
	v_lshl_add_u64 v[14:15], v[26:27], 0, s[0:1]
	s_add_i32 s0, s42, 0x8c00
	s_mov_b32 s1, m0
	s_mov_b32 m0, s0
	s_nop 0
	global_load_lds_dwordx4 v[14:15], off
	s_mov_b32 m0, s1
	s_mov_b64 s[0:1], 0x51800
	v_lshl_add_u64 v[14:15], v[26:27], 0, s[0:1]
	s_add_i32 s18, s42, 0x9000
	v_cndmask_b32_e64 v23, 0, 1, s[10:11]
	s_andn2_b64 vcc, exec, s[10:11]
	s_mov_b32 s10, m0
	s_mov_b32 m0, s18
	s_nop 0
	global_load_lds_dwordx4 v[14:15], off
	s_mov_b32 m0, s10
	v_cmp_ne_u32_e64 s[0:1], 1, v23
	s_cbranch_vccnz .LBB0_659
	s_mov_b64 s[10:11], 0x51c00
	v_lshl_add_u64 v[14:15], v[26:27], 0, s[10:11]
	s_add_i32 s10, s42, 0x9400
	s_mov_b32 s11, m0
	s_mov_b32 m0, s10
	s_nop 0
	global_load_lds_dwordx4 v[14:15], off
	s_mov_b32 m0, s11
.LBB0_659:
	s_mov_b64 s[10:11], 0xa0000
	v_lshl_add_u64 v[30:31], v[26:27], 0, s[10:11]
	s_add_i32 s19, s42, 0xf000
	s_mov_b32 s10, m0
	s_mov_b32 m0, s19
	s_nop 0
	global_load_lds_dwordx4 v[30:31], off
	s_mov_b32 m0, s10
	s_mov_b64 s[10:11], 0xa0400
	v_lshl_add_u64 v[30:31], v[26:27], 0, s[10:11]
	s_add_i32 s10, s42, 0xf400
	s_mov_b32 s11, m0
	s_mov_b32 m0, s10
	s_nop 0
	global_load_lds_dwordx4 v[30:31], off
	s_mov_b32 m0, s11
	s_mov_b64 s[10:11], 0xa0800
	v_lshl_add_u64 v[30:31], v[26:27], 0, s[10:11]
	s_add_i32 s10, s42, 0xf800
	s_mov_b32 s11, m0
	s_mov_b32 m0, s10
	s_nop 0
	global_load_lds_dwordx4 v[30:31], off
	s_mov_b32 m0, s11
	s_mov_b64 s[10:11], 0xa0c00
	v_lshl_add_u64 v[30:31], v[26:27], 0, s[10:11]
	s_add_i32 s10, s42, 0xfc00
	s_mov_b32 s11, m0
	s_mov_b32 m0, s10
	s_nop 0
	global_load_lds_dwordx4 v[30:31], off
	s_mov_b32 m0, s11
	s_mov_b64 s[10:11], 0xa1000
	v_lshl_add_u64 v[30:31], v[26:27], 0, s[10:11]
	s_add_i32 s10, s42, 0x10000
	s_mov_b32 s11, m0
	s_mov_b32 m0, s10
	s_nop 0
	global_load_lds_dwordx4 v[30:31], off
	s_mov_b32 m0, s11
	s_mov_b64 s[10:11], 0xa1400
	v_lshl_add_u64 v[30:31], v[26:27], 0, s[10:11]
	s_add_i32 s10, s42, 0x10400
	s_mov_b32 s11, m0
	s_mov_b32 m0, s10
	s_nop 0
	global_load_lds_dwordx4 v[30:31], off
	s_mov_b32 m0, s11
	s_mov_b64 s[10:11], 0xa1800
	v_lshl_add_u64 v[30:31], v[26:27], 0, s[10:11]
	s_add_i32 s10, s42, 0x10800
	s_mov_b32 s11, m0
	s_mov_b32 m0, s10
	s_nop 0
	global_load_lds_dwordx4 v[30:31], off
	s_mov_b32 m0, s11
	s_lshl_b32 s18, s2, 6
	v_lshlrev_b32_e32 v14, 4, v28
	s_mov_b64 s[10:11], -1
	s_and_b64 vcc, exec, s[8:9]
	v_readlane_b32 s96, v247, 24
	s_cbranch_vccz .LBB0_661
	s_waitcnt vmcnt(14)
	s_mov_b64 s[10:11], 0
.LBB0_661:
	s_andn2_b64 vcc, exec, s[10:11]
	s_cbranch_vccnz .LBB0_663
	s_mov_b64 s[10:11], 0xa1c00
	v_lshl_add_u64 v[26:27], v[26:27], 0, s[10:11]
	s_add_i32 s10, s19, 0x1c00
	s_mov_b32 s11, m0
	s_mov_b32 m0, s10
	s_nop 0
	global_load_lds_dwordx4 v[26:27], off
	s_mov_b32 m0, s11
	s_waitcnt vmcnt(16)

; #define SCAN_BAR() do { asm volatile("" ::: "memory"); __builtin_amdgcn_s_barrier(); asm volatile("" ::: "memory"); } while (0)
; #define SCAN_ISSUE(n, slot) do { const unsigned char* s_ = src + (size_t)(n) * step_stride; LAS unsigned char* d_ = lds + (slot) * SR_SLOT + p0 * 1024; \
;         _Pragma("unroll") for (int i_ = 0; i_ < 7; ++i_) glds16_asm(s_ + i_ * 1024, d_ + i_ * 1024, true  ); \
;         if (lw < 2) glds16_asm(s_ + 7 * 1024, d_ + 7 * 1024, true); } while (0)
; #define SCAN_ZISSUE(n) do { const unsigned char* z_ = zsrc + (size_t)(n) * 64 * 2048; LAS unsigned char* d_ = lds + ZT_OFF + ((n) & 1) * 8192 + (2 * lw) * 1024; \
;         glds16_asm(z_, d_, false); glds16_asm(z_ + 8 * 2048, d_ + 1024, false); } while (0)
; __device__ __forceinline__ void scan_prompt_wg(const Params& P, LAS unsigned char* lds, int s, int h, int wave, int lane) {
;     ...
;             if (n < NST) {
;                 asm volatile("s_waitcnt lgkmcnt(0)" ::: "memory");
;                 if (n + 1 < NST) SCAN_ZISSUE(n + 1);
;                 if (n + 3 < NST) SCAN_ISSUE(n + 3, slot);
;                 if (n >= 2 && n + 3 < NST) { if (lw < 2) asm volatile("s_waitcnt vmcnt(20)" ::: "memory"); else asm volatile("s_waitcnt vmcnt(18)" ::: "memory"); }
;                 else asm volatile("s_waitcnt vmcnt(0)" ::: "memory");
;                 slot = (slot == SR_NS - 1) ? 0 : slot + 1;
;                 SCAN_BAR();
.LBB0_678:
	s_mul_i32 s20, s2, 0x7800
	v_lshl_add_u64 v[28:29], v[18:19], 0, s[12:13]
	s_add_i32 s38, s42, s20
	s_mov_b32 s20, m0
	s_mov_b32 m0, s38
	s_nop 0
	global_load_lds_dwordx4 v[28:29], off
	s_mov_b32 m0, s20
	v_lshl_add_u64 v[28:29], v[18:19], 0, s[14:15]
	s_add_i32 s20, s38, 0x400
	s_mov_b32 s21, m0
	s_mov_b32 m0, s20
	s_nop 0
	global_load_lds_dwordx4 v[28:29], off
	s_mov_b32 m0, s21
	v_lshl_add_u64 v[28:29], v[18:19], 0, s[16:17]
	s_add_i32 s20, s38, 0x800
	s_mov_b32 s21, m0
	s_mov_b32 m0, s20
	s_nop 0
	global_load_lds_dwordx4 v[28:29], off
	s_mov_b32 m0, s21
	v_lshl_add_u64 v[28:29], v[18:19], 0, s[18:19]
	s_add_i32 s20, s38, 0xc00
	s_mov_b32 s21, m0
	s_mov_b32 m0, s20
	s_nop 0
	global_load_lds_dwordx4 v[28:29], off
	s_mov_b32 m0, s21
	v_lshl_add_u64 v[28:29], v[18:19], 0, s[24:25]
	s_add_i32 s20, s38, 0x1000
	s_mov_b32 s21, m0
	s_mov_b32 m0, s20
	s_nop 0
	global_load_lds_dwordx4 v[28:29], off
	s_mov_b32 m0, s21
	v_lshl_add_u64 v[28:29], v[18:19], 0, s[26:27]
	s_add_i32 s20, s38, 0x1400
	s_mov_b32 s21, m0
	s_mov_b32 m0, s20
	s_nop 0
	global_load_lds_dwordx4 v[28:29], off
	s_mov_b32 m0, s21
	v_lshl_add_u64 v[28:29], v[18:19], 0, s[28:29]
	s_add_i32 s20, s38, 0x1800
	s_mov_b32 s21, m0
	s_mov_b32 m0, s20
	s_nop 0
	global_load_lds_dwordx4 v[28:29], off
	s_mov_b32 m0, s21
	s_and_b64 vcc, exec, s[0:1]
	s_cbranch_vccnz .LBB0_680
	v_lshl_add_u64 v[28:29], v[18:19], 0, s[30:31]
	s_add_i32 s20, s38, 0x1c00
	s_mov_b32 s21, m0
	s_mov_b32 m0, s20
	s_nop 0
	global_load_lds_dwordx4 v[28:29], off
	s_mov_b32 m0, s21
